# attention K fragment prefetch depth reduced from 4 to 3 LDS reads in flight (fourth buffer joins the V fragment ring)
# baseline (speedup 1.0000x reference)
; #define LAS __attribute__((address_space(3)))
; #define SBAR() __builtin_amdgcn_sched_barrier(0)
; __device__ __forceinline__ void qkt(f32x16& p0, f32x16& p1, LAS const unsigned char* Ks, const bf16x8* qr, LAS const unsigned char* qt, int r32, int hi) {
;     p0 = (f32x16){}; p1 = (f32x16){};
; #pragma unroll
;     for (int d0 = 0; d0 < 12; ++d0) { const int cb = (d0 * 16 + hi * 8) * 2;
;         const bf16x8 b0 = *(const LAS bf16x8*)(Ks + KSWZ(r32, cb));
;         const bf16x8 b1 = *(const LAS bf16x8*)(Ks + KSWZ(32 + r32, cb));
;         const bf16x8 qf = d0 < QREG ? qr[d0 < QREG ? d0 : 0] : *(const LAS bf16x8*)(qt + (d0 - QREG) * 1024);
;         p0 = __builtin_amdgcn_mfma_f32_32x32x16_bf16(b0, qf, p0, 0, 0, 0);
;         p1 = __builtin_amdgcn_mfma_f32_32x32x16_bf16(b1, qf, p1, 0, 0, 0);
;         if ((d0 & 3) == 3) SBAR(); }
; }
; __device__ __forceinline__ void expP(f32x16& p0, f32x16& p1, float MB) {
; #pragma unroll
;     for (int r = 0; r < 16; ++r) p0[r] = __builtin_amdgcn_exp2f(p0[r] - MB);
; #pragma unroll
;     for (int r = 0; r < 16; ++r) p1[r] = __builtin_amdgcn_exp2f(p1[r] - MB);
; }
; __device__ __forceinline__ void attn_unit(const bf16_t* __restrict__ Qb, const bf16_t* __restrict__ Kh, const bf16_t* __restrict__ Vh, bf16_t* __restrict__ Ob,
;                                           LAS unsigned char* lds, float MB, int tid, int nrows, int t0, int t1, float* part, float* partl) {
;     ...
;     for (int j = t0; j < t1; ++j) {
;         const int b = (j - t0) & 1; const bool more = (j + 1 < t1);
;         if (more) { if (b) SDMA((j + 1) * KVBLK, 0); else SDMA((j + 1) * KVBLK, 1); }
;         if (act) {
;         SBAR(); qkt(p0, p1, K_lds + b * SHM_K, qr, qt, r32, hi);
;         expP(p0, p1, MB);
;         if (j == NT - 1) maskLast(p0, p1);
;         finishP(p0, p1, l_reg, pa0, pa1, pa2, pa3); SBAR();
.Latt_st2:
	s_andn2_b64 vcc, exec, s[50:51]
	s_cbranch_vccnz .Latt_inactive
	ds_read_b128 v[216:219], v213 offset:32768
	ds_read_b128 v[224:227], v214 offset:32768
	ds_read_b128 v[240:243], v213 offset:32896
	v_readfirstlane_b32 s70, v206
	s_nop 3
	s_cmpk_eq_i32 s66, 0x80
	s_cselect_b32 s66, 0x7f800000, s70
	s_add_i32 s67, s52, 64
	s_lshl_b32 s68, s67, 13
	s_mov_b32 s69, 0
	s_mul_i32 s43, s67, 0x1800
	s_add_u32 s70, s54, s43
	s_addc_u32 s71, s55, 0
	s_add_u32 s68, s56, s68
	s_addc_u32 s69, s57, s69
	s_add_i32 s53, s65, 2
	s_cmp_ge_u32 s53, 3
	s_cselect_b32 s42, 3, 0
	s_sub_i32 s53, s53, s42
	s_cmp_eq_u32 s53, 2
	s_cselect_b32 s42, 0x5000, 0
	s_cselect_b32 s43, 0xd000, 0
	s_mul_i32 s67, s53, 0x6000
	s_add_i32 s42, s42, s67
	s_add_i32 s42, s42, 0x8000
	s_add_i32 s42, s58, s42
	s_lshl_b32 s67, s53, 14
	s_add_i32 s43, s43, s67
	s_add_i32 s43, s58, s43
	s_waitcnt lgkmcnt(2)
	v_mfma_f32_16x16x32_bf16 v[64:67], v[216:219], v[96:99], 0
	v_mfma_f32_16x16x32_bf16 v[72:75], v[216:219], v[120:123], 0
	ds_read_b128 v[216:219], v214 offset:32896
	s_waitcnt lgkmcnt(2)
	v_mfma_f32_16x16x32_bf16 v[64:67], v[224:227], v[100:103], v[64:67]
	v_mfma_f32_16x16x32_bf16 v[72:75], v[224:227], v[124:127], v[72:75]
	ds_read_b128 v[224:227], v213 offset:33024
	s_waitcnt lgkmcnt(2)
	v_mfma_f32_16x16x32_bf16 v[64:67], v[240:243], v[104:107], v[64:67]
	v_lshl_add_u64 v[166:167], s[70:71], 0, v[156:157]
	s_mov_b32 m0, s42
	s_nop 0
	global_load_lds_dwordx4 v[166:167], off
	v_mfma_f32_16x16x32_bf16 v[72:75], v[240:243], v[128:131], v[72:75]
	ds_read_b128 v[240:243], v214 offset:33024
	s_waitcnt lgkmcnt(2)
	v_mfma_f32_16x16x32_bf16 v[64:67], v[216:219], v[108:111], v[64:67]
	v_mfma_f32_16x16x32_bf16 v[72:75], v[216:219], v[132:135], v[72:75]
	ds_read_b128 v[216:219], v213 offset:38912
	s_waitcnt lgkmcnt(2)
	v_mfma_f32_16x16x32_bf16 v[64:67], v[224:227], v[112:115], v[64:67]
	v_mfma_f32_16x16x32_bf16 v[72:75], v[224:227], v[136:139], v[72:75]
	ds_read_b128 v[224:227], v214 offset:38912
	s_waitcnt lgkmcnt(2)
	v_mfma_f32_16x16x32_bf16 v[64:67], v[240:243], v[116:119], v[64:67]
	v_mfma_f32_16x16x32_bf16 v[72:75], v[240:243], v[140:143], v[72:75]
	ds_read_b128 v[240:243], v213 offset:39040
	s_waitcnt lgkmcnt(2)
	v_mfma_f32_16x16x32_bf16 v[68:71], v[216:219], v[96:99], 0
	v_mfma_f32_16x16x32_bf16 v[76:79], v[216:219], v[120:123], 0
	ds_read_b128 v[216:219], v214 offset:39040
	s_waitcnt lgkmcnt(2)
	v_mfma_f32_16x16x32_bf16 v[68:71], v[224:227], v[100:103], v[68:71]
	v_mfma_f32_16x16x32_bf16 v[76:79], v[224:227], v[124:127], v[76:79]
	ds_read_b128 v[224:227], v213 offset:39168
	s_waitcnt lgkmcnt(2)
	v_mfma_f32_16x16x32_bf16 v[68:71], v[240:243], v[104:107], v[68:71]
	v_mfma_f32_16x16x32_bf16 v[76:79], v[240:243], v[128:131], v[76:79]
	ds_read_b128 v[240:243], v214 offset:39168
	s_waitcnt lgkmcnt(2)
	v_mfma_f32_16x16x32_bf16 v[68:71], v[216:219], v[108:111], v[68:71]
	v_mfma_f32_16x16x32_bf16 v[76:79], v[216:219], v[132:135], v[76:79]
	ds_read_b128 v[216:219], v213 offset:45056
	s_waitcnt lgkmcnt(2)
	v_mfma_f32_16x16x32_bf16 v[68:71], v[224:227], v[112:115], v[68:71]
	v_lshl_add_u64 v[166:167], s[70:71], 0, v[158:159]
	s_add_i32 m0, s42, 0x2000
	s_nop 0
	global_load_lds_dwordx4 v[166:167], off
	v_mfma_f32_16x16x32_bf16 v[76:79], v[224:227], v[136:139], v[76:79]
	ds_read_b128 v[224:227], v214 offset:45056
	s_waitcnt lgkmcnt(2)
	v_mfma_f32_16x16x32_bf16 v[68:71], v[240:243], v[116:119], v[68:71]
	v_mfma_f32_16x16x32_bf16 v[76:79], v[240:243], v[140:143], v[76:79]
	ds_read_b128 v[240:243], v213 offset:45184
	s_cmp_eq_u32 s66, 0
	s_cbranch_scc1 .Latt_fast
	v_sub_f32_e32 v64, v64, v206
	v_sub_f32_e32 v65, v65, v206
	v_exp_f32_e32 v64, v64
	s_waitcnt lgkmcnt(2)
	v_mfma_f32_16x16x32_bf16 v[80:83], v[216:219], v[96:99], 0
	v_sub_f32_e32 v66, v66, v206
	v_exp_f32_e32 v65, v65
	v_sub_f32_e32 v67, v67, v206
	v_mfma_f32_16x16x32_bf16 v[88:91], v[216:219], v[120:123], 0
	ds_read_b128 v[216:219], v214 offset:45184
	v_exp_f32_e32 v66, v66
	v_subrev_f32_e32 v68, s66, v68
	v_exp_f32_e32 v67, v67
	s_waitcnt lgkmcnt(2)
	v_mfma_f32_16x16x32_bf16 v[80:83], v[224:227], v[100:103], v[80:83]
	v_add_f32_e32 v146, v64, v65
	v_subrev_f32_e32 v69, s66, v69
	v_exp_f32_e32 v68, v68
	v_mfma_f32_16x16x32_bf16 v[88:91], v[224:227], v[124:127], v[88:91]
	ds_read_b128 v[224:227], v213 offset:45312
	v_add_f32_e32 v146, v66, v146
	v_subrev_f32_e32 v70, s66, v70
	v_exp_f32_e32 v69, v69
	s_waitcnt lgkmcnt(2)
	v_mfma_f32_16x16x32_bf16 v[80:83], v[240:243], v[104:107], v[80:83]
	v_add_f32_e32 v146, v67, v146
	v_subrev_f32_e32 v71, s66, v71
	v_exp_f32_e32 v70, v70
	v_mfma_f32_16x16x32_bf16 v[88:91], v[240:243], v[128:131], v[88:91]
	ds_read_b128 v[240:243], v214 offset:45312
	v_add_f32_e32 v146, v68, v146
	v_exp_f32_e32 v71, v71
	s_waitcnt lgkmcnt(2)
	v_mfma_f32_16x16x32_bf16 v[80:83], v[216:219], v[108:111], v[80:83]
	v_add_f32_e32 v146, v69, v146
	v_add_f32_e32 v146, v70, v146
	v_mfma_f32_16x16x32_bf16 v[88:91], v[216:219], v[132:135], v[88:91]
	ds_read_b128 v[216:219], v213 offset:51200
	v_add_f32_e32 v146, v71, v146
	v_cvt_pk_bf16_f32 v64, v64, v65
	s_waitcnt lgkmcnt(2)
	v_mfma_f32_16x16x32_bf16 v[80:83], v[224:227], v[112:115], v[80:83]
	v_cvt_pk_bf16_f32 v65, v66, v67
	v_cvt_pk_bf16_f32 v66, v68, v69
	v_mfma_f32_16x16x32_bf16 v[88:91], v[224:227], v[136:139], v[88:91]
	ds_read_b128 v[224:227], v214 offset:51200
	v_cvt_pk_bf16_f32 v67, v70, v71
	v_sub_f32_e32 v72, v72, v206
	ds_read_b128 v[68:71], v213 offset:51328
	s_waitcnt lgkmcnt(3)
	v_mfma_f32_16x16x32_bf16 v[80:83], v[240:243], v[116:119], v[80:83]
	v_sub_f32_e32 v73, v73, v206
	v_exp_f32_e32 v72, v72
	v_mfma_f32_16x16x32_bf16 v[88:91], v[240:243], v[140:143], v[88:91]
	ds_read_b128 v[240:243], v214 offset:51328
	v_sub_f32_e32 v74, v74, v206
	v_exp_f32_e32 v73, v73
	s_waitcnt lgkmcnt(3)
; #define SBAR() __builtin_amdgcn_sched_barrier(0)
; __device__ __forceinline__ void pv_d0(f32x16* o, int vb, bf16x8 pa0, bf16x8 pa1, bf16x8 pa2, bf16x8 pa3) {
;     VBlk A, B;
;     pv_load<0>(A, vb); pv_load<1>(B, vb);
;     asm volatile("s_waitcnt lgkmcnt(8)" ::: "memory"); SBAR(); pv_mma(o[0], A, pa0, pa1, pa2, pa3); SBAR();
;     pv_load<2>(A, vb);
;     asm volatile("s_waitcnt lgkmcnt(8)" ::: "memory"); SBAR(); pv_mma(o[1], B, pa0, pa1, pa2, pa3); SBAR();
;     pv_load<3>(B, vb);
;     asm volatile("s_waitcnt lgkmcnt(8)" ::: "memory"); SBAR(); pv_mma(o[2], A, pa0, pa1, pa2, pa3); SBAR();
; __device__ __forceinline__ void expP(f32x16& p0, f32x16& p1, float MB) {
; #pragma unroll
;     for (int r = 0; r < 16; ++r) p0[r] = __builtin_amdgcn_exp2f(p0[r] - MB);
; #pragma unroll
;     for (int r = 0; r < 16; ++r) p1[r] = __builtin_amdgcn_exp2f(p1[r] - MB);
; }
; __device__ __forceinline__ void maskLast(f32x16& p0, f32x16& p1) {
; #pragma unroll
;     for (int r = 8; r < 16; ++r) p0[r] = 0.f;
; #pragma unroll
;     for (int r = 0; r < 16; ++r) p1[r] = 0.f;
; }
; __device__ __forceinline__ void finishP(const f32x16& p0, const f32x16& p1, float& l_reg, bf16x8& pa0, bf16x8& pa1, bf16x8& pa2, bf16x8& pa3) {
;     float ps = 0.f;
; #pragma unroll
;     for (int r = 0; r < 16; ++r) ps += p0[r];
; #pragma unroll
;     for (int r = 0; r < 16; ++r) ps += p1[r];
;     l_reg += ps;
;     ...
;     PK4(p0, 0, pa0); PK4(p0, 8, pa1); PK4(p1, 0, pa2); PK4(p1, 8, pa3);
	v_mfma_f32_16x16x32_bf16 v[84:87], v[216:219], v[96:99], 0
	v_lshl_add_u64 v[166:167], s[70:71], 0, v[160:161]
	s_add_i32 m0, s42, 0x4000
	s_nop 0
	global_load_lds_dwordx4 v[166:167], off
	v_sub_f32_e32 v75, v75, v206
	v_exp_f32_e32 v74, v74
	v_mfma_f32_16x16x32_bf16 v[92:95], v[216:219], v[120:123], 0
	ds_read_b128 v[216:219], v213 offset:51456
	v_subrev_f32_e32 v76, s66, v76
	v_exp_f32_e32 v75, v75
	s_waitcnt lgkmcnt(3)
	v_mfma_f32_16x16x32_bf16 v[84:87], v[224:227], v[100:103], v[84:87]
	v_add_f32_e32 v148, v72, v73
	v_subrev_f32_e32 v77, s66, v77
	v_mfma_f32_16x16x32_bf16 v[92:95], v[224:227], v[124:127], v[92:95]
	ds_read_b128 v[224:227], v214 offset:51456
	v_exp_f32_e32 v76, v76
	v_add_f32_e32 v148, v74, v148
	s_waitcnt lgkmcnt(3)
	v_mfma_f32_16x16x32_bf16 v[84:87], v[68:71], v[104:107], v[84:87]
	v_subrev_f32_e32 v78, s66, v78
	v_exp_f32_e32 v77, v77
	v_mfma_f32_16x16x32_bf16 v[92:95], v[68:71], v[128:131], v[92:95]
	ds_read_b64_tr_b16 v[244:245], v147 offset:0
	ds_read_b64_tr_b16 v[246:247], v147 offset:4096
	v_add_f32_e32 v148, v75, v148
	v_subrev_f32_e32 v79, s66, v79
	s_waitcnt lgkmcnt(4)
	v_mfma_f32_16x16x32_bf16 v[84:87], v[240:243], v[108:111], v[84:87]
	v_exp_f32_e32 v78, v78
	v_add_f32_e32 v148, v76, v148
	v_mfma_f32_16x16x32_bf16 v[92:95], v[240:243], v[132:135], v[92:95]
	ds_read_b64_tr_b16 v[68:69], v147 offset:256
	ds_read_b64_tr_b16 v[70:71], v147 offset:4352
	v_exp_f32_e32 v79, v79
	v_add_f32_e32 v148, v77, v148
	s_waitcnt lgkmcnt(5)
	v_mfma_f32_16x16x32_bf16 v[84:87], v[216:219], v[112:115], v[84:87]
	v_add_f32_e32 v148, v78, v148
	v_add_f32_e32 v148, v79, v148
	v_mfma_f32_16x16x32_bf16 v[92:95], v[216:219], v[136:139], v[92:95]
	ds_read_b64_tr_b16 v[240:241], v147 offset:512
	ds_read_b64_tr_b16 v[242:243], v147 offset:4608
	v_cvt_pk_bf16_f32 v72, v72, v73
	v_cvt_pk_bf16_f32 v73, v74, v75
	s_waitcnt lgkmcnt(6)
	v_mfma_f32_16x16x32_bf16 v[84:87], v[224:227], v[116:119], v[84:87]
	v_cvt_pk_bf16_f32 v74, v76, v77
	v_cvt_pk_bf16_f32 v75, v78, v79
	ds_read_b64_tr_b16 v[216:217], v147 offset:768
	ds_read_b64_tr_b16 v[218:219], v147 offset:4864
	v_mfma_f32_16x16x32_bf16 v[92:95], v[224:227], v[140:143], v[92:95]
	ds_read_b64_tr_b16 v[76:77], v147 offset:1024
	ds_read_b64_tr_b16 v[78:79], v147 offset:5120
	ds_read_b64_tr_b16 v[224:225], v147 offset:1280
	ds_read_b64_tr_b16 v[226:227], v147 offset:5376
	v_subrev_f32_e32 v80, s66, v80
	v_subrev_f32_e32 v81, s66, v81
	v_exp_f32_e32 v80, v80
	v_subrev_f32_e32 v82, s66, v82
	s_waitcnt lgkmcnt(10)
	v_mfma_f32_16x16x32_bf16 v[0:3], v[64:67], v[244:247], v[0:3]
	v_exp_f32_e32 v81, v81
	v_subrev_f32_e32 v83, s66, v83
	v_exp_f32_e32 v82, v82
	v_add_f32_e32 v146, v80, v146
	v_mfma_f32_16x16x32_bf16 v[32:35], v[72:75], v[244:247], v[32:35]
	ds_read_b64_tr_b16 v[244:245], v147 offset:1536
	ds_read_b64_tr_b16 v[246:247], v147 offset:5632
	v_subrev_f32_e32 v84, s66, v84
	v_exp_f32_e32 v83, v83
	v_add_f32_e32 v146, v81, v146
	v_subrev_f32_e32 v85, s66, v85
	s_waitcnt lgkmcnt(10)
	v_mfma_f32_16x16x32_bf16 v[4:7], v[64:67], v[68:71], v[4:7]
	v_exp_f32_e32 v84, v84
	v_add_f32_e32 v146, v82, v146
	v_subrev_f32_e32 v86, s66, v86
	v_exp_f32_e32 v85, v85
	v_mfma_f32_16x16x32_bf16 v[36:39], v[72:75], v[68:71], v[36:39]
	ds_read_b64_tr_b16 v[68:69], v147 offset:1792
	ds_read_b64_tr_b16 v[70:71], v147 offset:5888
	v_add_f32_e32 v146, v83, v146
	v_subrev_f32_e32 v87, s66, v87
	v_exp_f32_e32 v86, v86
	v_add_f32_e32 v146, v84, v146
	s_waitcnt lgkmcnt(10)
	v_mfma_f32_16x16x32_bf16 v[8:11], v[64:67], v[240:243], v[8:11]
	v_lshl_add_u64 v[166:167], s[68:69], 0, v[162:163]
	s_mov_b32 m0, s43
	v_lshl_add_u64 v[166:167], v[166:167], 0, s[20:21]
	global_load_lds_dwordx4 v[166:167], off
	v_exp_f32_e32 v87, v87
	v_add_f32_e32 v146, v85, v146
	v_add_f32_e32 v146, v86, v146
	v_add_f32_e32 v146, v87, v146
	v_mfma_f32_16x16x32_bf16 v[40:43], v[72:75], v[240:243], v[40:43]
	ds_read_b64_tr_b16 v[240:241], v147 offset:8192
	ds_read_b64_tr_b16 v[242:243], v147 offset:12288
	v_cvt_pk_bf16_f32 v80, v80, v81
	v_cvt_pk_bf16_f32 v81, v82, v83
	v_cvt_pk_bf16_f32 v82, v84, v85
	v_cvt_pk_bf16_f32 v83, v86, v87
	s_waitcnt lgkmcnt(10)
; #define SBAR() __builtin_amdgcn_sched_barrier(0)
; __device__ __forceinline__ void pv_mma(f32x16& od, const VBlk& b, bf16x8 pa0, bf16x8 pa1, bf16x8 pa2, bf16x8 pa3) {
;     ...
;     od = __builtin_amdgcn_mfma_f32_32x32x16_bf16(pa0, PK(b.l0, b.h0), od, 0, 0, 0);
;     od = __builtin_amdgcn_mfma_f32_32x32x16_bf16(pa1, PK(b.l1, b.h1), od, 0, 0, 0);
;     od = __builtin_amdgcn_mfma_f32_32x32x16_bf16(pa2, PK(b.l2, b.h2), od, 0, 0, 0);
;     od = __builtin_amdgcn_mfma_f32_32x32x16_bf16(pa3, PK(b.l3, b.h3), od, 0, 0, 0);
;     ...
; }
; __device__ __forceinline__ void pv_d0(f32x16* o, int vb, bf16x8 pa0, bf16x8 pa1, bf16x8 pa2, bf16x8 pa3) {
;     VBlk A, B;
;     pv_load<0>(A, vb); pv_load<1>(B, vb);
;     asm volatile("s_waitcnt lgkmcnt(8)" ::: "memory"); SBAR(); pv_mma(o[0], A, pa0, pa1, pa2, pa3); SBAR();
;     pv_load<2>(A, vb);
;     asm volatile("s_waitcnt lgkmcnt(8)" ::: "memory"); SBAR(); pv_mma(o[1], B, pa0, pa1, pa2, pa3); SBAR();
;     pv_load<3>(B, vb);
;     asm volatile("s_waitcnt lgkmcnt(8)" ::: "memory"); SBAR(); pv_mma(o[2], A, pa0, pa1, pa2, pa3); SBAR();
;     asm volatile("s_waitcnt lgkmcnt(0)" ::: "memory"); SBAR(); pv_mma(o[3], B, pa0, pa1, pa2, pa3); SBAR();
; }
	v_mfma_f32_16x16x32_bf16 v[12:15], v[64:67], v[216:219], v[12:15]
	v_add_f32_e32 v155, v155, v146
	v_subrev_f32_e32 v88, s66, v88
	v_subrev_f32_e32 v89, s66, v89
	v_exp_f32_e32 v88, v88
	ds_read_b64_tr_b16 v[84:85], v147 offset:8448
	ds_read_b64_tr_b16 v[86:87], v147 offset:12544
	v_mfma_f32_16x16x32_bf16 v[44:47], v[72:75], v[216:219], v[44:47]
	ds_read_b64_tr_b16 v[216:217], v147 offset:8704
	ds_read_b64_tr_b16 v[218:219], v147 offset:12800
	v_subrev_f32_e32 v90, s66, v90
	v_exp_f32_e32 v89, v89
	v_subrev_f32_e32 v91, s66, v91
	v_exp_f32_e32 v90, v90
	s_waitcnt lgkmcnt(12)
	v_mfma_f32_16x16x32_bf16 v[16:19], v[64:67], v[76:79], v[16:19]
	v_add_f32_e32 v148, v88, v148
	v_subrev_f32_e32 v92, s66, v92
	v_exp_f32_e32 v91, v91
	v_add_f32_e32 v148, v89, v148
	v_mfma_f32_16x16x32_bf16 v[48:51], v[72:75], v[76:79], v[48:51]
	ds_read_b64_tr_b16 v[76:77], v147 offset:8960
	ds_read_b64_tr_b16 v[78:79], v147 offset:13056
	v_subrev_f32_e32 v93, s66, v93
	v_exp_f32_e32 v92, v92
	v_add_f32_e32 v148, v90, v148
	s_waitcnt lgkmcnt(12)
	v_mfma_f32_16x16x32_bf16 v[20:23], v[64:67], v[224:227], v[20:23]
	v_subrev_f32_e32 v94, s66, v94
	v_exp_f32_e32 v93, v93
	v_add_f32_e32 v148, v91, v148
	v_mfma_f32_16x16x32_bf16 v[52:55], v[72:75], v[224:227], v[52:55]
	ds_read_b64_tr_b16 v[224:225], v147 offset:9216
	ds_read_b64_tr_b16 v[226:227], v147 offset:13312
	v_subrev_f32_e32 v95, s66, v95
	v_exp_f32_e32 v94, v94
	v_add_f32_e32 v148, v92, v148
	s_waitcnt lgkmcnt(12)
	v_mfma_f32_16x16x32_bf16 v[24:27], v[64:67], v[244:247], v[24:27]
	v_exp_f32_e32 v95, v95
	v_add_f32_e32 v148, v93, v148
	v_add_f32_e32 v148, v94, v148
	v_mfma_f32_16x16x32_bf16 v[56:59], v[72:75], v[244:247], v[56:59]
	ds_read_b64_tr_b16 v[244:245], v147 offset:9472
	ds_read_b64_tr_b16 v[246:247], v147 offset:13568
	v_add_f32_e32 v148, v95, v148
	v_cvt_pk_bf16_f32 v88, v88, v89
	v_cvt_pk_bf16_f32 v89, v90, v91
	s_waitcnt lgkmcnt(12)
	v_mfma_f32_16x16x32_bf16 v[28:31], v[64:67], v[68:71], v[28:31]
	v_cvt_pk_bf16_f32 v90, v92, v93
	v_cvt_pk_bf16_f32 v91, v94, v95
	v_add_f32_e32 v149, v149, v148
	ds_read_b64_tr_b16 v[92:93], v147 offset:9728
	ds_read_b64_tr_b16 v[94:95], v147 offset:13824
	v_mfma_f32_16x16x32_bf16 v[60:63], v[72:75], v[68:71], v[60:63]
	s_waitcnt lgkmcnt(12)
	v_mfma_f32_16x16x32_bf16 v[0:3], v[80:83], v[240:243], v[0:3]
	v_mfma_f32_16x16x32_bf16 v[32:35], v[88:91], v[240:243], v[32:35]
	ds_read_b64_tr_b16 v[68:69], v147 offset:9984
	ds_read_b64_tr_b16 v[70:71], v147 offset:14080
	s_waitcnt lgkmcnt(12)
	v_mfma_f32_16x16x32_bf16 v[4:7], v[80:83], v[84:87], v[4:7]
	v_mfma_f32_16x16x32_bf16 v[36:39], v[88:91], v[84:87], v[36:39]
	s_waitcnt lgkmcnt(10)
	v_mfma_f32_16x16x32_bf16 v[8:11], v[80:83], v[216:219], v[8:11]
	v_lshl_add_u64 v[166:167], s[68:69], 0, v[164:165]
	s_add_i32 m0, s43, 0x2000
	v_lshl_add_u64 v[166:167], v[166:167], 0, s[20:21]
	global_load_lds_dwordx4 v[166:167], off
	v_mfma_f32_16x16x32_bf16 v[40:43], v[88:91], v[216:219], v[40:43]
	s_waitcnt lgkmcnt(8)
	v_mfma_f32_16x16x32_bf16 v[12:15], v[80:83], v[76:79], v[12:15]
	v_mfma_f32_16x16x32_bf16 v[44:47], v[88:91], v[76:79], v[44:47]
	s_waitcnt lgkmcnt(6)
	v_mfma_f32_16x16x32_bf16 v[16:19], v[80:83], v[224:227], v[16:19]
	v_mfma_f32_16x16x32_bf16 v[48:51], v[88:91], v[224:227], v[48:51]
	s_waitcnt lgkmcnt(4)
	v_mfma_f32_16x16x32_bf16 v[20:23], v[80:83], v[244:247], v[20:23]
	v_mfma_f32_16x16x32_bf16 v[52:55], v[88:91], v[244:247], v[52:55]
	s_waitcnt lgkmcnt(2)
	v_mfma_f32_16x16x32_bf16 v[24:27], v[80:83], v[92:95], v[24:27]
	v_mfma_f32_16x16x32_bf16 v[56:59], v[88:91], v[92:95], v[56:59]
	s_waitcnt lgkmcnt(0)
	v_mfma_f32_16x16x32_bf16 v[28:31], v[80:83], v[68:71], v[28:31]
	v_mfma_f32_16x16x32_bf16 v[60:63], v[88:91], v[68:71], v[60:63]
	s_mov_b32 s71, 1
	s_branch .LBB0_137

; #define LAS __attribute__((address_space(3)))
; #define SBAR() __builtin_amdgcn_sched_barrier(0)
; __device__ __forceinline__ void qkt(f32x16& p0, f32x16& p1, LAS const unsigned char* Ks, const bf16x8* qr, LAS const unsigned char* qt, int r32, int hi) {
;     p0 = (f32x16){}; p1 = (f32x16){};
; #pragma unroll
;     for (int d0 = 0; d0 < 12; ++d0) { const int cb = (d0 * 16 + hi * 8) * 2;
;         const bf16x8 b0 = *(const LAS bf16x8*)(Ks + KSWZ(r32, cb));
;         const bf16x8 b1 = *(const LAS bf16x8*)(Ks + KSWZ(32 + r32, cb));
;         const bf16x8 qf = d0 < QREG ? qr[d0 < QREG ? d0 : 0] : *(const LAS bf16x8*)(qt + (d0 - QREG) * 1024);
;         p0 = __builtin_amdgcn_mfma_f32_32x32x16_bf16(b0, qf, p0, 0, 0, 0);
;         p1 = __builtin_amdgcn_mfma_f32_32x32x16_bf16(b1, qf, p1, 0, 0, 0);
;         if ((d0 & 3) == 3) SBAR(); }
; }
; __device__ __forceinline__ void expP(f32x16& p0, f32x16& p1, float MB) {
; #pragma unroll
;     for (int r = 0; r < 16; ++r) p0[r] = __builtin_amdgcn_exp2f(p0[r] - MB);
; #pragma unroll
;     for (int r = 0; r < 16; ++r) p1[r] = __builtin_amdgcn_exp2f(p1[r] - MB);
; }
; __device__ __forceinline__ void maskLast(f32x16& p0, f32x16& p1) {
; #pragma unroll
;     for (int r = 8; r < 16; ++r) p0[r] = 0.f;
; #pragma unroll
;     for (int r = 0; r < 16; ++r) p1[r] = 0.f;
; }
; __device__ __forceinline__ void finishP(const f32x16& p0, const f32x16& p1, float& l_reg, bf16x8& pa0, bf16x8& pa1, bf16x8& pa2, bf16x8& pa3) {
;     float ps = 0.f;
; #pragma unroll
;     for (int r = 0; r < 16; ++r) ps += p0[r];
; #pragma unroll
;     for (int r = 0; r < 16; ++r) ps += p1[r];
;     l_reg += ps;
;     ...
;     PK4(p0, 0, pa0); PK4(p0, 8, pa1); PK4(p1, 0, pa2); PK4(p1, 8, pa3);
.Latt_fast:
	v_exp_f32_e32 v64, v64
	v_exp_f32_e32 v65, v65
	s_waitcnt lgkmcnt(2)
	v_mfma_f32_16x16x32_bf16 v[80:83], v[216:219], v[96:99], 0
	v_exp_f32_e32 v66, v66
	v_exp_f32_e32 v67, v67
	v_mfma_f32_16x16x32_bf16 v[88:91], v[216:219], v[120:123], 0
	ds_read_b128 v[216:219], v214 offset:45184
	v_add_f32_e32 v146, v64, v65
	v_exp_f32_e32 v68, v68
	s_waitcnt lgkmcnt(2)
	v_mfma_f32_16x16x32_bf16 v[80:83], v[224:227], v[100:103], v[80:83]
	v_add_f32_e32 v146, v66, v146
	v_exp_f32_e32 v69, v69
	v_mfma_f32_16x16x32_bf16 v[88:91], v[224:227], v[124:127], v[88:91]
	ds_read_b128 v[224:227], v213 offset:45312
	v_add_f32_e32 v146, v67, v146
	v_exp_f32_e32 v70, v70
	s_waitcnt lgkmcnt(2)
	v_mfma_f32_16x16x32_bf16 v[80:83], v[240:243], v[104:107], v[80:83]
	v_add_f32_e32 v146, v68, v146
	v_exp_f32_e32 v71, v71
	v_mfma_f32_16x16x32_bf16 v[88:91], v[240:243], v[128:131], v[88:91]
	ds_read_b128 v[240:243], v214 offset:45312
	v_add_f32_e32 v146, v69, v146
	v_add_f32_e32 v146, v70, v146
	s_waitcnt lgkmcnt(2)
	v_mfma_f32_16x16x32_bf16 v[80:83], v[216:219], v[108:111], v[80:83]
	v_add_f32_e32 v146, v71, v146
	v_cvt_pk_bf16_f32 v64, v64, v65
	v_mfma_f32_16x16x32_bf16 v[88:91], v[216:219], v[132:135], v[88:91]
	ds_read_b128 v[216:219], v213 offset:51200
	v_cvt_pk_bf16_f32 v65, v66, v67
	v_cvt_pk_bf16_f32 v66, v68, v69
	s_waitcnt lgkmcnt(2)
	v_mfma_f32_16x16x32_bf16 v[80:83], v[224:227], v[112:115], v[80:83]
	v_cvt_pk_bf16_f32 v67, v70, v71
	v_exp_f32_e32 v72, v72
	ds_read_b128 v[68:71], v214 offset:51200
	v_mfma_f32_16x16x32_bf16 v[88:91], v[224:227], v[136:139], v[88:91]
	ds_read_b128 v[224:227], v213 offset:51328
	v_exp_f32_e32 v73, v73
	v_exp_f32_e32 v74, v74
	s_waitcnt lgkmcnt(3)
	v_mfma_f32_16x16x32_bf16 v[80:83], v[240:243], v[116:119], v[80:83]
	v_exp_f32_e32 v75, v75
	v_add_f32_e32 v148, v72, v73
	v_mfma_f32_16x16x32_bf16 v[88:91], v[240:243], v[140:143], v[88:91]
	ds_read_b128 v[240:243], v214 offset:51328
	v_exp_f32_e32 v76, v76
	v_add_f32_e32 v148, v74, v148
	s_waitcnt lgkmcnt(3)
	v_mfma_f32_16x16x32_bf16 v[84:87], v[216:219], v[96:99], 0
	v_lshl_add_u64 v[166:167], s[70:71], 0, v[160:161]
	s_add_i32 m0, s42, 0x4000
	s_nop 0
	global_load_lds_dwordx4 v[166:167], off
	v_exp_f32_e32 v77, v77
	v_add_f32_e32 v148, v75, v148
	v_mfma_f32_16x16x32_bf16 v[92:95], v[216:219], v[120:123], 0
	ds_read_b128 v[216:219], v213 offset:51456
	v_exp_f32_e32 v78, v78
	s_waitcnt lgkmcnt(3)
	v_mfma_f32_16x16x32_bf16 v[84:87], v[68:71], v[100:103], v[84:87]
	v_add_f32_e32 v148, v76, v148
	v_mfma_f32_16x16x32_bf16 v[92:95], v[68:71], v[124:127], v[92:95]
	ds_read_b128 v[68:71], v214 offset:51456
	v_exp_f32_e32 v79, v79
	s_waitcnt lgkmcnt(3)
	v_mfma_f32_16x16x32_bf16 v[84:87], v[224:227], v[104:107], v[84:87]
	v_add_f32_e32 v148, v77, v148
	v_mfma_f32_16x16x32_bf16 v[92:95], v[224:227], v[128:131], v[92:95]
	ds_read_b64_tr_b16 v[244:245], v147 offset:0
	ds_read_b64_tr_b16 v[246:247], v147 offset:4096
	v_add_f32_e32 v148, v78, v148
	s_waitcnt lgkmcnt(4)
	v_mfma_f32_16x16x32_bf16 v[84:87], v[240:243], v[108:111], v[84:87]
	v_add_f32_e32 v148, v79, v148
	v_mfma_f32_16x16x32_bf16 v[92:95], v[240:243], v[132:135], v[92:95]
	ds_read_b64_tr_b16 v[224:225], v147 offset:256
	ds_read_b64_tr_b16 v[226:227], v147 offset:4352
	v_cvt_pk_bf16_f32 v72, v72, v73
	s_waitcnt lgkmcnt(5)
	v_mfma_f32_16x16x32_bf16 v[84:87], v[216:219], v[112:115], v[84:87]
	v_cvt_pk_bf16_f32 v73, v74, v75
	v_mfma_f32_16x16x32_bf16 v[92:95], v[216:219], v[136:139], v[92:95]
	ds_read_b64_tr_b16 v[240:241], v147 offset:512
	ds_read_b64_tr_b16 v[242:243], v147 offset:4608
	v_cvt_pk_bf16_f32 v74, v76, v77
	s_waitcnt lgkmcnt(6)
	v_mfma_f32_16x16x32_bf16 v[84:87], v[68:71], v[116:119], v[84:87]
	v_cvt_pk_bf16_f32 v75, v78, v79
	ds_read_b64_tr_b16 v[216:217], v147 offset:768
	ds_read_b64_tr_b16 v[218:219], v147 offset:4864
	v_mfma_f32_16x16x32_bf16 v[92:95], v[68:71], v[140:143], v[92:95]
	ds_read_b64_tr_b16 v[76:77], v147 offset:1024
	ds_read_b64_tr_b16 v[78:79], v147 offset:5120
	ds_read_b64_tr_b16 v[68:69], v147 offset:1280
	ds_read_b64_tr_b16 v[70:71], v147 offset:5376
	v_exp_f32_e32 v80, v80
	v_exp_f32_e32 v81, v81
	v_exp_f32_e32 v82, v82
	s_waitcnt lgkmcnt(10)
	v_mfma_f32_16x16x32_bf16 v[0:3], v[64:67], v[244:247], v[0:3]
	v_add_f32_e32 v146, v80, v146
	v_exp_f32_e32 v83, v83
	v_add_f32_e32 v146, v81, v146
	v_mfma_f32_16x16x32_bf16 v[32:35], v[72:75], v[244:247], v[32:35]
	ds_read_b64_tr_b16 v[244:245], v147 offset:1536
	ds_read_b64_tr_b16 v[246:247], v147 offset:5632
	v_exp_f32_e32 v84, v84
	v_add_f32_e32 v146, v82, v146
	v_exp_f32_e32 v85, v85
	s_waitcnt lgkmcnt(10)
; #define SBAR() __builtin_amdgcn_sched_barrier(0)
; __device__ __forceinline__ void pv_mma(f32x16& od, const VBlk& b, bf16x8 pa0, bf16x8 pa1, bf16x8 pa2, bf16x8 pa3) {
;     ...
;     od = __builtin_amdgcn_mfma_f32_32x32x16_bf16(pa0, PK(b.l0, b.h0), od, 0, 0, 0);
;     od = __builtin_amdgcn_mfma_f32_32x32x16_bf16(pa1, PK(b.l1, b.h1), od, 0, 0, 0);
;     od = __builtin_amdgcn_mfma_f32_32x32x16_bf16(pa2, PK(b.l2, b.h2), od, 0, 0, 0);
;     od = __builtin_amdgcn_mfma_f32_32x32x16_bf16(pa3, PK(b.l3, b.h3), od, 0, 0, 0);
;     ...
; }
; __device__ __forceinline__ void pv_d0(f32x16* o, int vb, bf16x8 pa0, bf16x8 pa1, bf16x8 pa2, bf16x8 pa3) {
;     VBlk A, B;
;     pv_load<0>(A, vb); pv_load<1>(B, vb);
;     asm volatile("s_waitcnt lgkmcnt(8)" ::: "memory"); SBAR(); pv_mma(o[0], A, pa0, pa1, pa2, pa3); SBAR();
;     pv_load<2>(A, vb);
;     asm volatile("s_waitcnt lgkmcnt(8)" ::: "memory"); SBAR(); pv_mma(o[1], B, pa0, pa1, pa2, pa3); SBAR();
;     pv_load<3>(B, vb);
;     asm volatile("s_waitcnt lgkmcnt(8)" ::: "memory"); SBAR(); pv_mma(o[2], A, pa0, pa1, pa2, pa3); SBAR();
;     asm volatile("s_waitcnt lgkmcnt(0)" ::: "memory"); SBAR(); pv_mma(o[3], B, pa0, pa1, pa2, pa3); SBAR();
; }
	v_mfma_f32_16x16x32_bf16 v[4:7], v[64:67], v[224:227], v[4:7]
	v_add_f32_e32 v146, v83, v146
	v_exp_f32_e32 v86, v86
	v_add_f32_e32 v146, v84, v146
	v_mfma_f32_16x16x32_bf16 v[36:39], v[72:75], v[224:227], v[36:39]
	ds_read_b64_tr_b16 v[224:225], v147 offset:1792
	ds_read_b64_tr_b16 v[226:227], v147 offset:5888
	v_exp_f32_e32 v87, v87
	v_add_f32_e32 v146, v85, v146
	v_add_f32_e32 v146, v86, v146
	s_waitcnt lgkmcnt(10)
	v_mfma_f32_16x16x32_bf16 v[8:11], v[64:67], v[240:243], v[8:11]
	v_lshl_add_u64 v[166:167], s[68:69], 0, v[162:163]
	s_mov_b32 m0, s43
	v_lshl_add_u64 v[166:167], v[166:167], 0, s[20:21]
	global_load_lds_dwordx4 v[166:167], off
	v_add_f32_e32 v146, v87, v146
	v_cvt_pk_bf16_f32 v80, v80, v81
	v_cvt_pk_bf16_f32 v81, v82, v83
	v_mfma_f32_16x16x32_bf16 v[40:43], v[72:75], v[240:243], v[40:43]
	ds_read_b64_tr_b16 v[240:241], v147 offset:8192
	ds_read_b64_tr_b16 v[242:243], v147 offset:12288
	v_cvt_pk_bf16_f32 v82, v84, v85
	v_cvt_pk_bf16_f32 v83, v86, v87
	v_add_f32_e32 v155, v155, v146
	ds_read_b64_tr_b16 v[84:85], v147 offset:8448
	ds_read_b64_tr_b16 v[86:87], v147 offset:12544
	s_waitcnt lgkmcnt(12)
	v_mfma_f32_16x16x32_bf16 v[12:15], v[64:67], v[216:219], v[12:15]
	v_exp_f32_e32 v88, v88
	v_exp_f32_e32 v89, v89
	v_exp_f32_e32 v90, v90
	v_mfma_f32_16x16x32_bf16 v[44:47], v[72:75], v[216:219], v[44:47]
	ds_read_b64_tr_b16 v[216:217], v147 offset:8704
	ds_read_b64_tr_b16 v[218:219], v147 offset:12800
	v_add_f32_e32 v148, v88, v148
	v_exp_f32_e32 v91, v91
	v_add_f32_e32 v148, v89, v148
	s_waitcnt lgkmcnt(12)
	v_mfma_f32_16x16x32_bf16 v[16:19], v[64:67], v[76:79], v[16:19]
	v_exp_f32_e32 v92, v92
	v_add_f32_e32 v148, v90, v148
	v_exp_f32_e32 v93, v93
	v_mfma_f32_16x16x32_bf16 v[48:51], v[72:75], v[76:79], v[48:51]
	ds_read_b64_tr_b16 v[76:77], v147 offset:8960
	ds_read_b64_tr_b16 v[78:79], v147 offset:13056
	v_add_f32_e32 v148, v91, v148
	v_exp_f32_e32 v94, v94
	s_waitcnt lgkmcnt(12)
	v_mfma_f32_16x16x32_bf16 v[20:23], v[64:67], v[68:71], v[20:23]
	v_add_f32_e32 v148, v92, v148
	v_exp_f32_e32 v95, v95
	v_mfma_f32_16x16x32_bf16 v[52:55], v[72:75], v[68:71], v[52:55]
	ds_read_b64_tr_b16 v[68:69], v147 offset:9216
	ds_read_b64_tr_b16 v[70:71], v147 offset:13312
	v_add_f32_e32 v148, v93, v148
	v_add_f32_e32 v148, v94, v148
	s_waitcnt lgkmcnt(12)
	v_mfma_f32_16x16x32_bf16 v[24:27], v[64:67], v[244:247], v[24:27]
	v_add_f32_e32 v148, v95, v148
	v_cvt_pk_bf16_f32 v88, v88, v89
	v_mfma_f32_16x16x32_bf16 v[56:59], v[72:75], v[244:247], v[56:59]
	ds_read_b64_tr_b16 v[244:245], v147 offset:9472
	ds_read_b64_tr_b16 v[246:247], v147 offset:13568
	v_cvt_pk_bf16_f32 v89, v90, v91
	v_cvt_pk_bf16_f32 v90, v92, v93
	s_waitcnt lgkmcnt(12)
	v_mfma_f32_16x16x32_bf16 v[28:31], v[64:67], v[224:227], v[28:31]
	v_cvt_pk_bf16_f32 v91, v94, v95
	v_add_f32_e32 v149, v149, v148
	ds_read_b64_tr_b16 v[92:93], v147 offset:9728
	ds_read_b64_tr_b16 v[94:95], v147 offset:13824
	v_mfma_f32_16x16x32_bf16 v[60:63], v[72:75], v[224:227], v[60:63]
	s_waitcnt lgkmcnt(12)
	v_mfma_f32_16x16x32_bf16 v[0:3], v[80:83], v[240:243], v[0:3]
	v_mfma_f32_16x16x32_bf16 v[32:35], v[88:91], v[240:243], v[32:35]
	ds_read_b64_tr_b16 v[224:225], v147 offset:9984
	ds_read_b64_tr_b16 v[226:227], v147 offset:14080
	s_waitcnt lgkmcnt(12)
	v_mfma_f32_16x16x32_bf16 v[4:7], v[80:83], v[84:87], v[4:7]
	v_mfma_f32_16x16x32_bf16 v[36:39], v[88:91], v[84:87], v[36:39]
	s_waitcnt lgkmcnt(10)
	v_mfma_f32_16x16x32_bf16 v[8:11], v[80:83], v[216:219], v[8:11]
	v_lshl_add_u64 v[166:167], s[68:69], 0, v[164:165]
	s_add_i32 m0, s43, 0x2000
	v_lshl_add_u64 v[166:167], v[166:167], 0, s[20:21]
	global_load_lds_dwordx4 v[166:167], off
	v_mfma_f32_16x16x32_bf16 v[40:43], v[88:91], v[216:219], v[40:43]
	s_waitcnt lgkmcnt(8)
	v_mfma_f32_16x16x32_bf16 v[12:15], v[80:83], v[76:79], v[12:15]
	v_mfma_f32_16x16x32_bf16 v[44:47], v[88:91], v[76:79], v[44:47]
	s_waitcnt lgkmcnt(6)
	v_mfma_f32_16x16x32_bf16 v[16:19], v[80:83], v[68:71], v[16:19]
	v_mfma_f32_16x16x32_bf16 v[48:51], v[88:91], v[68:71], v[48:51]
	s_waitcnt lgkmcnt(4)
	v_mfma_f32_16x16x32_bf16 v[20:23], v[80:83], v[244:247], v[20:23]
	v_mfma_f32_16x16x32_bf16 v[52:55], v[88:91], v[244:247], v[52:55]
	s_waitcnt lgkmcnt(2)
	v_mfma_f32_16x16x32_bf16 v[24:27], v[80:83], v[92:95], v[24:27]
	v_mfma_f32_16x16x32_bf16 v[56:59], v[88:91], v[92:95], v[56:59]
	s_waitcnt lgkmcnt(0)
	v_mfma_f32_16x16x32_bf16 v[28:31], v[80:83], v[224:227], v[28:31]
	v_mfma_f32_16x16x32_bf16 v[60:63], v[88:91], v[224:227], v[60:63]
	s_mov_b32 s71, 1
	s_branch .LBB0_137
